# ssd_passC + mlstm_passC staging loops unrolled into straight-line code with all trips' loads in flight (counted waits)
# speedup vs baseline: 1.0774x; 1.0038x over previous
.LBB0_926:
	s_waitcnt vmcnt(4)
	s_lshl_b32 s8, s30, 2
	v_mov_b32_e32 v114, v7
	v_ashrrev_i32_e32 v115, 6, v114
	v_lshlrev_b32_e32 v116, 2, v115
	ds_read_b32 v116, v116 offset:58368
	v_mul_lo_u32 v117, v115, s87
	v_add_lshl_u32 v117, v117, v0, 1
	v_lshl_add_u32 v118, v115, 1, v6
	v_mov_b64_e32 v[120:121], s[94:95]
	global_load_dword v125, v[2:3], off
	v_lshl_add_u64 v[2:3], v[2:3], 0, s[10:11]
	global_load_dword v126, v[4:5], off
	v_lshl_add_u64 v[4:5], v[4:5], 0, s[10:11]
	v_add_u32_e32 v128, 0x100, v7
	v_ashrrev_i32_e32 v129, 6, v128
	v_lshlrev_b32_e32 v130, 2, v129
	ds_read_b32 v130, v130 offset:58368
	v_mul_lo_u32 v131, v129, s87
	v_add_lshl_u32 v131, v131, v0, 1
	v_lshl_add_u32 v132, v129, 1, v6
	v_mov_b64_e32 v[134:135], s[94:95]
	global_load_dword v139, v[2:3], off
	v_lshl_add_u64 v[2:3], v[2:3], 0, s[10:11]
	global_load_dword v140, v[4:5], off
	v_lshl_add_u64 v[4:5], v[4:5], 0, s[10:11]
	v_add_u32_e32 v152, 0x200, v7
	v_ashrrev_i32_e32 v153, 6, v152
	v_lshlrev_b32_e32 v154, 2, v153
	ds_read_b32 v154, v154 offset:58368
	v_mul_lo_u32 v155, v153, s87
	v_add_lshl_u32 v155, v155, v0, 1
	v_lshl_add_u32 v156, v153, 1, v6
	v_mov_b64_e32 v[158:159], s[94:95]
	global_load_dword v163, v[2:3], off
	v_lshl_add_u64 v[2:3], v[2:3], 0, s[10:11]
	global_load_dword v164, v[4:5], off
	v_lshl_add_u64 v[4:5], v[4:5], 0, s[10:11]
	v_add_u32_e32 v204, 0x300, v7
	v_ashrrev_i32_e32 v205, 6, v204
	v_lshlrev_b32_e32 v206, 2, v205
	ds_read_b32 v206, v206 offset:58368
	v_mul_lo_u32 v207, v205, s87
	v_add_lshl_u32 v207, v207, v0, 1
	v_lshl_add_u32 v208, v205, 1, v6
	v_mov_b64_e32 v[210:211], s[94:95]
	global_load_dword v215, v[2:3], off
	v_lshl_add_u64 v[2:3], v[2:3], 0, s[10:11]
	global_load_dword v216, v[4:5], off
	v_lshl_add_u64 v[4:5], v[4:5], 0, s[10:11]
	s_waitcnt lgkmcnt(3)
	v_mad_i64_i32 v[120:121], s[4:5], v116, s6, v[120:121]
	v_lshl_add_u64 v[120:121], v[120:121], 0, s[8:9]
	v_lshl_add_u64 v[120:121], v[120:121], 0, v[148:149]
	v_add_co_u32_e32 v120, vcc, s7, v120
	s_nop 1
	v_addc_co_u32_e32 v121, vcc, 0, v121, vcc
	global_load_dword v122, v[120:121], off offset:-992
	global_load_dword v123, v[120:121], off offset:32
	global_load_dword v124, v[120:121], off offset:1056
	s_waitcnt lgkmcnt(2)
	v_mad_i64_i32 v[134:135], s[4:5], v130, s6, v[134:135]
	v_lshl_add_u64 v[134:135], v[134:135], 0, s[8:9]
	v_lshl_add_u64 v[134:135], v[134:135], 0, v[148:149]
	v_add_co_u32_e32 v134, vcc, s7, v134
	s_nop 1
	v_addc_co_u32_e32 v135, vcc, 0, v135, vcc
	global_load_dword v136, v[134:135], off offset:-992
	global_load_dword v137, v[134:135], off offset:32
	global_load_dword v138, v[134:135], off offset:1056
	s_waitcnt lgkmcnt(1)
	v_mad_i64_i32 v[158:159], s[4:5], v154, s6, v[158:159]
	v_lshl_add_u64 v[158:159], v[158:159], 0, s[8:9]
	v_lshl_add_u64 v[158:159], v[158:159], 0, v[148:149]
	v_add_co_u32_e32 v158, vcc, s7, v158
	s_nop 1
	v_addc_co_u32_e32 v159, vcc, 0, v159, vcc
	global_load_dword v160, v[158:159], off offset:-992
	global_load_dword v161, v[158:159], off offset:32
	global_load_dword v162, v[158:159], off offset:1056
	s_waitcnt lgkmcnt(0)
	v_mad_i64_i32 v[210:211], s[4:5], v206, s6, v[210:211]
	v_lshl_add_u64 v[210:211], v[210:211], 0, s[8:9]
	v_lshl_add_u64 v[210:211], v[210:211], 0, v[148:149]
	v_add_co_u32_e32 v210, vcc, s7, v210
	s_nop 1
	v_addc_co_u32_e32 v211, vcc, 0, v211, vcc
	global_load_dword v212, v[210:211], off offset:-992
	global_load_dword v213, v[210:211], off offset:32
	global_load_dword v214, v[210:211], off offset:1056
	s_waitcnt vmcnt(11)
	v_bfe_u32 v119, v122, 16, 1
	v_add3_u32 v122, v122, v119, s52
	ds_write_b16_d16_hi v117, v122
	s_waitcnt vmcnt(10)
	v_mul_f32_e32 v123, 0x3e000000, v123
	v_bfe_u32 v119, v123, 16, 1
	v_add3_u32 v123, v123, v119, s52
	ds_write_b16_d16_hi v117, v123 offset:9216
	s_waitcnt vmcnt(9)
	v_bfe_u32 v119, v124, 16, 1
	v_add3_u32 v124, v124, v119, s52
	ds_write_b16_d16_hi v118, v124 offset:27648
	v_bfe_u32 v119, v125, 16, 1
	v_add3_u32 v125, v125, v119, s52
	ds_write_b16_d16_hi v117, v125 offset:36864
	v_bfe_u32 v119, v126, 16, 1
	v_add3_u32 v126, v126, v119, s52
	ds_write_b16_d16_hi v117, v126 offset:46080
	s_waitcnt vmcnt(8)
	v_bfe_u32 v133, v136, 16, 1
	v_add3_u32 v136, v136, v133, s52
	ds_write_b16_d16_hi v131, v136
	s_waitcnt vmcnt(7)
	v_mul_f32_e32 v137, 0x3e000000, v137
	v_bfe_u32 v133, v137, 16, 1
	v_add3_u32 v137, v137, v133, s52
	ds_write_b16_d16_hi v131, v137 offset:9216
	s_waitcnt vmcnt(6)
	v_bfe_u32 v133, v138, 16, 1
	v_add3_u32 v138, v138, v133, s52
	ds_write_b16_d16_hi v132, v138 offset:27648
	v_bfe_u32 v133, v139, 16, 1
	v_add3_u32 v139, v139, v133, s52
	ds_write_b16_d16_hi v131, v139 offset:36864
	v_bfe_u32 v133, v140, 16, 1
	v_add3_u32 v140, v140, v133, s52
	ds_write_b16_d16_hi v131, v140 offset:46080
	s_waitcnt vmcnt(5)
	v_bfe_u32 v157, v160, 16, 1
	v_add3_u32 v160, v160, v157, s52
	ds_write_b16_d16_hi v155, v160
	s_waitcnt vmcnt(4)
	v_mul_f32_e32 v161, 0x3e000000, v161
	v_bfe_u32 v157, v161, 16, 1
	v_add3_u32 v161, v161, v157, s52
	ds_write_b16_d16_hi v155, v161 offset:9216
	s_waitcnt vmcnt(3)
	v_bfe_u32 v157, v162, 16, 1
	v_add3_u32 v162, v162, v157, s52
	ds_write_b16_d16_hi v156, v162 offset:27648
	v_bfe_u32 v157, v163, 16, 1
	v_add3_u32 v163, v163, v157, s52
	ds_write_b16_d16_hi v155, v163 offset:36864
	v_bfe_u32 v157, v164, 16, 1
	v_add3_u32 v164, v164, v157, s52
	ds_write_b16_d16_hi v155, v164 offset:46080
	s_waitcnt vmcnt(2)
	v_bfe_u32 v209, v212, 16, 1
	v_add3_u32 v212, v212, v209, s52
	ds_write_b16_d16_hi v207, v212
	s_waitcnt vmcnt(1)
	v_mul_f32_e32 v213, 0x3e000000, v213
	v_bfe_u32 v209, v213, 16, 1
	v_add3_u32 v213, v213, v209, s52
	ds_write_b16_d16_hi v207, v213 offset:9216
	s_waitcnt vmcnt(0)
	v_bfe_u32 v209, v214, 16, 1
	v_add3_u32 v214, v214, v209, s52
	ds_write_b16_d16_hi v208, v214 offset:27648
	v_bfe_u32 v209, v215, 16, 1
	v_add3_u32 v215, v215, v209, s52
	ds_write_b16_d16_hi v207, v215 offset:36864
	v_bfe_u32 v209, v216, 16, 1
	v_add3_u32 v216, v216, v209, s52
	ds_write_b16_d16_hi v207, v216 offset:46080
	v_add_u32_e32 v114, 0x400, v7
	v_ashrrev_i32_e32 v115, 6, v114
	v_lshlrev_b32_e32 v116, 2, v115
	ds_read_b32 v116, v116 offset:58368
	v_mul_lo_u32 v117, v115, s87
	v_add_lshl_u32 v117, v117, v0, 1
	v_lshl_add_u32 v118, v115, 1, v6
	v_mov_b64_e32 v[120:121], s[94:95]
	global_load_dword v125, v[2:3], off
	v_lshl_add_u64 v[2:3], v[2:3], 0, s[10:11]
	global_load_dword v126, v[4:5], off
	v_lshl_add_u64 v[4:5], v[4:5], 0, s[10:11]
	v_add_u32_e32 v128, 0x500, v7
	v_ashrrev_i32_e32 v129, 6, v128
	v_lshlrev_b32_e32 v130, 2, v129
	ds_read_b32 v130, v130 offset:58368
	v_mul_lo_u32 v131, v129, s87
	v_add_lshl_u32 v131, v131, v0, 1
	v_lshl_add_u32 v132, v129, 1, v6
	v_mov_b64_e32 v[134:135], s[94:95]
	global_load_dword v139, v[2:3], off
	v_lshl_add_u64 v[2:3], v[2:3], 0, s[10:11]
	global_load_dword v140, v[4:5], off
	v_lshl_add_u64 v[4:5], v[4:5], 0, s[10:11]
	v_add_u32_e32 v152, 0x600, v7
	v_ashrrev_i32_e32 v153, 6, v152
	v_lshlrev_b32_e32 v154, 2, v153
	ds_read_b32 v154, v154 offset:58368
	v_mul_lo_u32 v155, v153, s87
	v_add_lshl_u32 v155, v155, v0, 1
	v_lshl_add_u32 v156, v153, 1, v6
	v_mov_b64_e32 v[158:159], s[94:95]
	global_load_dword v163, v[2:3], off
	v_lshl_add_u64 v[2:3], v[2:3], 0, s[10:11]
	global_load_dword v164, v[4:5], off
	v_lshl_add_u64 v[4:5], v[4:5], 0, s[10:11]
	v_add_u32_e32 v204, 0x700, v7
	v_ashrrev_i32_e32 v205, 6, v204
	v_lshlrev_b32_e32 v206, 2, v205
	ds_read_b32 v206, v206 offset:58368
	v_mul_lo_u32 v207, v205, s87
	v_add_lshl_u32 v207, v207, v0, 1
	v_lshl_add_u32 v208, v205, 1, v6
	v_mov_b64_e32 v[210:211], s[94:95]
	global_load_dword v215, v[2:3], off
	v_lshl_add_u64 v[2:3], v[2:3], 0, s[10:11]
	global_load_dword v216, v[4:5], off
	v_lshl_add_u64 v[4:5], v[4:5], 0, s[10:11]
	s_waitcnt lgkmcnt(3)
	v_mad_i64_i32 v[120:121], s[4:5], v116, s6, v[120:121]
	v_lshl_add_u64 v[120:121], v[120:121], 0, s[8:9]
	v_lshl_add_u64 v[120:121], v[120:121], 0, v[148:149]
	v_add_co_u32_e32 v120, vcc, s7, v120
	s_nop 1
	v_addc_co_u32_e32 v121, vcc, 0, v121, vcc
	global_load_dword v122, v[120:121], off offset:-992
	global_load_dword v123, v[120:121], off offset:32
	global_load_dword v124, v[120:121], off offset:1056
	s_waitcnt lgkmcnt(2)
	v_mad_i64_i32 v[134:135], s[4:5], v130, s6, v[134:135]
	v_lshl_add_u64 v[134:135], v[134:135], 0, s[8:9]
	v_lshl_add_u64 v[134:135], v[134:135], 0, v[148:149]
	v_add_co_u32_e32 v134, vcc, s7, v134
	s_nop 1
	v_addc_co_u32_e32 v135, vcc, 0, v135, vcc
	global_load_dword v136, v[134:135], off offset:-992
	global_load_dword v137, v[134:135], off offset:32
	global_load_dword v138, v[134:135], off offset:1056
	s_waitcnt lgkmcnt(1)
	v_mad_i64_i32 v[158:159], s[4:5], v154, s6, v[158:159]
	v_lshl_add_u64 v[158:159], v[158:159], 0, s[8:9]
	v_lshl_add_u64 v[158:159], v[158:159], 0, v[148:149]
	v_add_co_u32_e32 v158, vcc, s7, v158
	s_nop 1
	v_addc_co_u32_e32 v159, vcc, 0, v159, vcc
	global_load_dword v160, v[158:159], off offset:-992
	global_load_dword v161, v[158:159], off offset:32
	global_load_dword v162, v[158:159], off offset:1056
	s_waitcnt lgkmcnt(0)
	v_mad_i64_i32 v[210:211], s[4:5], v206, s6, v[210:211]
	v_lshl_add_u64 v[210:211], v[210:211], 0, s[8:9]
	v_lshl_add_u64 v[210:211], v[210:211], 0, v[148:149]
	v_add_co_u32_e32 v210, vcc, s7, v210
	s_nop 1
	v_addc_co_u32_e32 v211, vcc, 0, v211, vcc
	global_load_dword v212, v[210:211], off offset:-992
	global_load_dword v213, v[210:211], off offset:32
	global_load_dword v214, v[210:211], off offset:1056
	s_waitcnt vmcnt(11)
	v_bfe_u32 v119, v122, 16, 1
	v_add3_u32 v122, v122, v119, s52
	ds_write_b16_d16_hi v117, v122
	s_waitcnt vmcnt(10)
	v_mul_f32_e32 v123, 0x3e000000, v123
	v_bfe_u32 v119, v123, 16, 1
	v_add3_u32 v123, v123, v119, s52
	ds_write_b16_d16_hi v117, v123 offset:9216
	s_waitcnt vmcnt(9)
	v_bfe_u32 v119, v124, 16, 1
	v_add3_u32 v124, v124, v119, s52
	ds_write_b16_d16_hi v118, v124 offset:27648
	v_bfe_u32 v119, v125, 16, 1
	v_add3_u32 v125, v125, v119, s52
	ds_write_b16_d16_hi v117, v125 offset:36864
	v_bfe_u32 v119, v126, 16, 1
	v_add3_u32 v126, v126, v119, s52
	ds_write_b16_d16_hi v117, v126 offset:46080
	s_waitcnt vmcnt(8)
	v_bfe_u32 v133, v136, 16, 1
	v_add3_u32 v136, v136, v133, s52
	ds_write_b16_d16_hi v131, v136
	s_waitcnt vmcnt(7)
	v_mul_f32_e32 v137, 0x3e000000, v137
	v_bfe_u32 v133, v137, 16, 1
	v_add3_u32 v137, v137, v133, s52
	ds_write_b16_d16_hi v131, v137 offset:9216
	s_waitcnt vmcnt(6)
	v_bfe_u32 v133, v138, 16, 1
	v_add3_u32 v138, v138, v133, s52
	ds_write_b16_d16_hi v132, v138 offset:27648
	v_bfe_u32 v133, v139, 16, 1
	v_add3_u32 v139, v139, v133, s52
	ds_write_b16_d16_hi v131, v139 offset:36864
	v_bfe_u32 v133, v140, 16, 1
	v_add3_u32 v140, v140, v133, s52
	ds_write_b16_d16_hi v131, v140 offset:46080
	s_waitcnt vmcnt(5)
	v_bfe_u32 v157, v160, 16, 1
	v_add3_u32 v160, v160, v157, s52
	ds_write_b16_d16_hi v155, v160
	s_waitcnt vmcnt(4)
	v_mul_f32_e32 v161, 0x3e000000, v161
	v_bfe_u32 v157, v161, 16, 1
	v_add3_u32 v161, v161, v157, s52
	ds_write_b16_d16_hi v155, v161 offset:9216
	s_waitcnt vmcnt(3)
	v_bfe_u32 v157, v162, 16, 1
	v_add3_u32 v162, v162, v157, s52
	ds_write_b16_d16_hi v156, v162 offset:27648
	v_bfe_u32 v157, v163, 16, 1
	v_add3_u32 v163, v163, v157, s52
	ds_write_b16_d16_hi v155, v163 offset:36864
	v_bfe_u32 v157, v164, 16, 1
	v_add3_u32 v164, v164, v157, s52
	ds_write_b16_d16_hi v155, v164 offset:46080
	s_waitcnt vmcnt(2)
	v_bfe_u32 v209, v212, 16, 1
	v_add3_u32 v212, v212, v209, s52
	ds_write_b16_d16_hi v207, v212
	s_waitcnt vmcnt(1)
	v_mul_f32_e32 v213, 0x3e000000, v213
	v_bfe_u32 v209, v213, 16, 1
	v_add3_u32 v213, v213, v209, s52
	ds_write_b16_d16_hi v207, v213 offset:9216
	s_waitcnt vmcnt(0)
	v_bfe_u32 v209, v214, 16, 1
	v_add3_u32 v214, v214, v209, s52
	ds_write_b16_d16_hi v208, v214 offset:27648
	v_bfe_u32 v209, v215, 16, 1
	v_add3_u32 v215, v215, v209, s52
	ds_write_b16_d16_hi v207, v215 offset:36864
	v_bfe_u32 v209, v216, 16, 1
	v_add3_u32 v216, v216, v209, s52
	ds_write_b16_d16_hi v207, v216 offset:46080
	v_add_u32_e32 v114, 0x800, v7
	v_ashrrev_i32_e32 v115, 6, v114
	v_lshlrev_b32_e32 v116, 2, v115
	ds_read_b32 v116, v116 offset:58368
	v_mul_lo_u32 v117, v115, s87
	v_add_lshl_u32 v117, v117, v0, 1
	v_lshl_add_u32 v118, v115, 1, v6
	v_mov_b64_e32 v[120:121], s[94:95]
	global_load_dword v125, v[2:3], off
	v_lshl_add_u64 v[2:3], v[2:3], 0, s[10:11]
	global_load_dword v126, v[4:5], off
	v_lshl_add_u64 v[4:5], v[4:5], 0, s[10:11]
	v_add_u32_e32 v128, 0x900, v7
	v_ashrrev_i32_e32 v129, 6, v128
	v_lshlrev_b32_e32 v130, 2, v129
	ds_read_b32 v130, v130 offset:58368
	v_mul_lo_u32 v131, v129, s87
	v_add_lshl_u32 v131, v131, v0, 1
	v_lshl_add_u32 v132, v129, 1, v6
	v_mov_b64_e32 v[134:135], s[94:95]
	global_load_dword v139, v[2:3], off
	v_lshl_add_u64 v[2:3], v[2:3], 0, s[10:11]
	global_load_dword v140, v[4:5], off
	v_lshl_add_u64 v[4:5], v[4:5], 0, s[10:11]
	v_add_u32_e32 v152, 0xa00, v7
	v_ashrrev_i32_e32 v153, 6, v152
	v_lshlrev_b32_e32 v154, 2, v153
	ds_read_b32 v154, v154 offset:58368
	v_mul_lo_u32 v155, v153, s87
	v_add_lshl_u32 v155, v155, v0, 1
	v_lshl_add_u32 v156, v153, 1, v6
	v_mov_b64_e32 v[158:159], s[94:95]
	global_load_dword v163, v[2:3], off
	v_lshl_add_u64 v[2:3], v[2:3], 0, s[10:11]
	global_load_dword v164, v[4:5], off
	v_lshl_add_u64 v[4:5], v[4:5], 0, s[10:11]
	v_add_u32_e32 v204, 0xb00, v7
	v_ashrrev_i32_e32 v205, 6, v204
	v_lshlrev_b32_e32 v206, 2, v205
	ds_read_b32 v206, v206 offset:58368
	v_mul_lo_u32 v207, v205, s87
	v_add_lshl_u32 v207, v207, v0, 1
	v_lshl_add_u32 v208, v205, 1, v6
	v_mov_b64_e32 v[210:211], s[94:95]
	global_load_dword v215, v[2:3], off
	v_lshl_add_u64 v[2:3], v[2:3], 0, s[10:11]
	global_load_dword v216, v[4:5], off
	v_lshl_add_u64 v[4:5], v[4:5], 0, s[10:11]
	s_waitcnt lgkmcnt(3)
	v_mad_i64_i32 v[120:121], s[4:5], v116, s6, v[120:121]
	v_lshl_add_u64 v[120:121], v[120:121], 0, s[8:9]
	v_lshl_add_u64 v[120:121], v[120:121], 0, v[148:149]
	v_add_co_u32_e32 v120, vcc, s7, v120
	s_nop 1
	v_addc_co_u32_e32 v121, vcc, 0, v121, vcc
	global_load_dword v122, v[120:121], off offset:-992
	global_load_dword v123, v[120:121], off offset:32
	global_load_dword v124, v[120:121], off offset:1056
	s_waitcnt lgkmcnt(2)
	v_mad_i64_i32 v[134:135], s[4:5], v130, s6, v[134:135]
	v_lshl_add_u64 v[134:135], v[134:135], 0, s[8:9]
	v_lshl_add_u64 v[134:135], v[134:135], 0, v[148:149]
	v_add_co_u32_e32 v134, vcc, s7, v134
	s_nop 1
	v_addc_co_u32_e32 v135, vcc, 0, v135, vcc
	global_load_dword v136, v[134:135], off offset:-992
	global_load_dword v137, v[134:135], off offset:32
	global_load_dword v138, v[134:135], off offset:1056
	s_waitcnt lgkmcnt(1)
	v_mad_i64_i32 v[158:159], s[4:5], v154, s6, v[158:159]
	v_lshl_add_u64 v[158:159], v[158:159], 0, s[8:9]
	v_lshl_add_u64 v[158:159], v[158:159], 0, v[148:149]
	v_add_co_u32_e32 v158, vcc, s7, v158
	s_nop 1
	v_addc_co_u32_e32 v159, vcc, 0, v159, vcc
	global_load_dword v160, v[158:159], off offset:-992
	global_load_dword v161, v[158:159], off offset:32
	global_load_dword v162, v[158:159], off offset:1056
	s_waitcnt lgkmcnt(0)
	v_mad_i64_i32 v[210:211], s[4:5], v206, s6, v[210:211]
	v_lshl_add_u64 v[210:211], v[210:211], 0, s[8:9]
	v_lshl_add_u64 v[210:211], v[210:211], 0, v[148:149]
	v_add_co_u32_e32 v210, vcc, s7, v210
	s_nop 1
	v_addc_co_u32_e32 v211, vcc, 0, v211, vcc
	global_load_dword v212, v[210:211], off offset:-992
	global_load_dword v213, v[210:211], off offset:32
	global_load_dword v214, v[210:211], off offset:1056
	s_waitcnt vmcnt(11)
	v_bfe_u32 v119, v122, 16, 1
	v_add3_u32 v122, v122, v119, s52
	ds_write_b16_d16_hi v117, v122
	s_waitcnt vmcnt(10)
	v_mul_f32_e32 v123, 0x3e000000, v123
	v_bfe_u32 v119, v123, 16, 1
	v_add3_u32 v123, v123, v119, s52
	ds_write_b16_d16_hi v117, v123 offset:9216
	s_waitcnt vmcnt(9)
	v_bfe_u32 v119, v124, 16, 1
	v_add3_u32 v124, v124, v119, s52
	ds_write_b16_d16_hi v118, v124 offset:27648
	v_bfe_u32 v119, v125, 16, 1
	v_add3_u32 v125, v125, v119, s52
	ds_write_b16_d16_hi v117, v125 offset:36864
	v_bfe_u32 v119, v126, 16, 1
	v_add3_u32 v126, v126, v119, s52
	ds_write_b16_d16_hi v117, v126 offset:46080
	s_waitcnt vmcnt(8)
	v_bfe_u32 v133, v136, 16, 1
	v_add3_u32 v136, v136, v133, s52
	ds_write_b16_d16_hi v131, v136
	s_waitcnt vmcnt(7)
	v_mul_f32_e32 v137, 0x3e000000, v137
	v_bfe_u32 v133, v137, 16, 1
	v_add3_u32 v137, v137, v133, s52
	ds_write_b16_d16_hi v131, v137 offset:9216
	s_waitcnt vmcnt(6)
	v_bfe_u32 v133, v138, 16, 1
	v_add3_u32 v138, v138, v133, s52
	ds_write_b16_d16_hi v132, v138 offset:27648
	v_bfe_u32 v133, v139, 16, 1
	v_add3_u32 v139, v139, v133, s52
	ds_write_b16_d16_hi v131, v139 offset:36864
	v_bfe_u32 v133, v140, 16, 1
	v_add3_u32 v140, v140, v133, s52
	ds_write_b16_d16_hi v131, v140 offset:46080
	s_waitcnt vmcnt(5)
	v_bfe_u32 v157, v160, 16, 1
	v_add3_u32 v160, v160, v157, s52
	ds_write_b16_d16_hi v155, v160
	s_waitcnt vmcnt(4)
	v_mul_f32_e32 v161, 0x3e000000, v161
	v_bfe_u32 v157, v161, 16, 1
	v_add3_u32 v161, v161, v157, s52
	ds_write_b16_d16_hi v155, v161 offset:9216
	s_waitcnt vmcnt(3)
	v_bfe_u32 v157, v162, 16, 1
	v_add3_u32 v162, v162, v157, s52
	ds_write_b16_d16_hi v156, v162 offset:27648
	v_bfe_u32 v157, v163, 16, 1
	v_add3_u32 v163, v163, v157, s52
	ds_write_b16_d16_hi v155, v163 offset:36864
	v_bfe_u32 v157, v164, 16, 1
	v_add3_u32 v164, v164, v157, s52
	ds_write_b16_d16_hi v155, v164 offset:46080
	s_waitcnt vmcnt(2)
	v_bfe_u32 v209, v212, 16, 1
	v_add3_u32 v212, v212, v209, s52
	ds_write_b16_d16_hi v207, v212
	s_waitcnt vmcnt(1)
	v_mul_f32_e32 v213, 0x3e000000, v213
	v_bfe_u32 v209, v213, 16, 1
	v_add3_u32 v213, v213, v209, s52
	ds_write_b16_d16_hi v207, v213 offset:9216
	s_waitcnt vmcnt(0)
	v_bfe_u32 v209, v214, 16, 1
	v_add3_u32 v214, v214, v209, s52
	ds_write_b16_d16_hi v208, v214 offset:27648
	v_bfe_u32 v209, v215, 16, 1
	v_add3_u32 v215, v215, v209, s52
	ds_write_b16_d16_hi v207, v215 offset:36864
	v_bfe_u32 v209, v216, 16, 1
	v_add3_u32 v216, v216, v209, s52
	ds_write_b16_d16_hi v207, v216 offset:46080
	v_add_u32_e32 v114, 0xc00, v7
	v_ashrrev_i32_e32 v115, 6, v114
	v_lshlrev_b32_e32 v116, 2, v115
	ds_read_b32 v116, v116 offset:58368
	v_mul_lo_u32 v117, v115, s87
	v_add_lshl_u32 v117, v117, v0, 1
	v_lshl_add_u32 v118, v115, 1, v6
	v_mov_b64_e32 v[120:121], s[94:95]
	global_load_dword v125, v[2:3], off
	v_lshl_add_u64 v[2:3], v[2:3], 0, s[10:11]
	global_load_dword v126, v[4:5], off
	v_lshl_add_u64 v[4:5], v[4:5], 0, s[10:11]
	v_add_u32_e32 v128, 0xd00, v7
	v_ashrrev_i32_e32 v129, 6, v128
	v_lshlrev_b32_e32 v130, 2, v129
	ds_read_b32 v130, v130 offset:58368
	v_mul_lo_u32 v131, v129, s87
	v_add_lshl_u32 v131, v131, v0, 1
	v_lshl_add_u32 v132, v129, 1, v6
	v_mov_b64_e32 v[134:135], s[94:95]
	global_load_dword v139, v[2:3], off
	v_lshl_add_u64 v[2:3], v[2:3], 0, s[10:11]
	global_load_dword v140, v[4:5], off
	v_lshl_add_u64 v[4:5], v[4:5], 0, s[10:11]
	v_add_u32_e32 v152, 0xe00, v7
	v_ashrrev_i32_e32 v153, 6, v152
	v_lshlrev_b32_e32 v154, 2, v153
	ds_read_b32 v154, v154 offset:58368
	v_mul_lo_u32 v155, v153, s87
	v_add_lshl_u32 v155, v155, v0, 1
	v_lshl_add_u32 v156, v153, 1, v6
	v_mov_b64_e32 v[158:159], s[94:95]
	global_load_dword v163, v[2:3], off
	v_lshl_add_u64 v[2:3], v[2:3], 0, s[10:11]
	global_load_dword v164, v[4:5], off
	v_lshl_add_u64 v[4:5], v[4:5], 0, s[10:11]
	v_add_u32_e32 v204, 0xf00, v7
	v_ashrrev_i32_e32 v205, 6, v204
	v_lshlrev_b32_e32 v206, 2, v205
	ds_read_b32 v206, v206 offset:58368
	v_mul_lo_u32 v207, v205, s87
	v_add_lshl_u32 v207, v207, v0, 1
	v_lshl_add_u32 v208, v205, 1, v6
	v_mov_b64_e32 v[210:211], s[94:95]
	global_load_dword v215, v[2:3], off
	v_lshl_add_u64 v[2:3], v[2:3], 0, s[10:11]
	global_load_dword v216, v[4:5], off
	v_lshl_add_u64 v[4:5], v[4:5], 0, s[10:11]
	s_waitcnt lgkmcnt(3)
	v_mad_i64_i32 v[120:121], s[4:5], v116, s6, v[120:121]
	v_lshl_add_u64 v[120:121], v[120:121], 0, s[8:9]
	v_lshl_add_u64 v[120:121], v[120:121], 0, v[148:149]
	v_add_co_u32_e32 v120, vcc, s7, v120
	s_nop 1
	v_addc_co_u32_e32 v121, vcc, 0, v121, vcc
	global_load_dword v122, v[120:121], off offset:-992
	global_load_dword v123, v[120:121], off offset:32
	global_load_dword v124, v[120:121], off offset:1056
	s_waitcnt lgkmcnt(2)
	v_mad_i64_i32 v[134:135], s[4:5], v130, s6, v[134:135]
	v_lshl_add_u64 v[134:135], v[134:135], 0, s[8:9]
	v_lshl_add_u64 v[134:135], v[134:135], 0, v[148:149]
	v_add_co_u32_e32 v134, vcc, s7, v134
	s_nop 1
	v_addc_co_u32_e32 v135, vcc, 0, v135, vcc
	global_load_dword v136, v[134:135], off offset:-992
	global_load_dword v137, v[134:135], off offset:32
	global_load_dword v138, v[134:135], off offset:1056
	s_waitcnt lgkmcnt(1)
	v_mad_i64_i32 v[158:159], s[4:5], v154, s6, v[158:159]
	v_lshl_add_u64 v[158:159], v[158:159], 0, s[8:9]
	v_lshl_add_u64 v[158:159], v[158:159], 0, v[148:149]
	v_add_co_u32_e32 v158, vcc, s7, v158
	s_nop 1
	v_addc_co_u32_e32 v159, vcc, 0, v159, vcc
	global_load_dword v160, v[158:159], off offset:-992
	global_load_dword v161, v[158:159], off offset:32
	global_load_dword v162, v[158:159], off offset:1056
	s_waitcnt lgkmcnt(0)
	v_mad_i64_i32 v[210:211], s[4:5], v206, s6, v[210:211]
	v_lshl_add_u64 v[210:211], v[210:211], 0, s[8:9]
	v_lshl_add_u64 v[210:211], v[210:211], 0, v[148:149]
	v_add_co_u32_e32 v210, vcc, s7, v210
	s_nop 1
	v_addc_co_u32_e32 v211, vcc, 0, v211, vcc
	global_load_dword v212, v[210:211], off offset:-992
	global_load_dword v213, v[210:211], off offset:32
	global_load_dword v214, v[210:211], off offset:1056
	s_waitcnt vmcnt(11)
	v_bfe_u32 v119, v122, 16, 1
	v_add3_u32 v122, v122, v119, s52
	ds_write_b16_d16_hi v117, v122
	s_waitcnt vmcnt(10)
	v_mul_f32_e32 v123, 0x3e000000, v123
	v_bfe_u32 v119, v123, 16, 1
	v_add3_u32 v123, v123, v119, s52
	ds_write_b16_d16_hi v117, v123 offset:9216
	s_waitcnt vmcnt(9)
	v_bfe_u32 v119, v124, 16, 1
	v_add3_u32 v124, v124, v119, s52
	ds_write_b16_d16_hi v118, v124 offset:27648
	v_bfe_u32 v119, v125, 16, 1
	v_add3_u32 v125, v125, v119, s52
	ds_write_b16_d16_hi v117, v125 offset:36864
	v_bfe_u32 v119, v126, 16, 1
	v_add3_u32 v126, v126, v119, s52
	ds_write_b16_d16_hi v117, v126 offset:46080
	s_waitcnt vmcnt(8)
	v_bfe_u32 v133, v136, 16, 1
	v_add3_u32 v136, v136, v133, s52
	ds_write_b16_d16_hi v131, v136
	s_waitcnt vmcnt(7)
	v_mul_f32_e32 v137, 0x3e000000, v137
	v_bfe_u32 v133, v137, 16, 1
	v_add3_u32 v137, v137, v133, s52
	ds_write_b16_d16_hi v131, v137 offset:9216
	s_waitcnt vmcnt(6)
	v_bfe_u32 v133, v138, 16, 1
	v_add3_u32 v138, v138, v133, s52
	ds_write_b16_d16_hi v132, v138 offset:27648
	v_bfe_u32 v133, v139, 16, 1
	v_add3_u32 v139, v139, v133, s52
	ds_write_b16_d16_hi v131, v139 offset:36864
	v_bfe_u32 v133, v140, 16, 1
	v_add3_u32 v140, v140, v133, s52
	ds_write_b16_d16_hi v131, v140 offset:46080
	s_waitcnt vmcnt(5)
	v_bfe_u32 v157, v160, 16, 1
	v_add3_u32 v160, v160, v157, s52
	ds_write_b16_d16_hi v155, v160
	s_waitcnt vmcnt(4)
	v_mul_f32_e32 v161, 0x3e000000, v161
	v_bfe_u32 v157, v161, 16, 1
	v_add3_u32 v161, v161, v157, s52
	ds_write_b16_d16_hi v155, v161 offset:9216
	s_waitcnt vmcnt(3)
	v_bfe_u32 v157, v162, 16, 1
	v_add3_u32 v162, v162, v157, s52
	ds_write_b16_d16_hi v156, v162 offset:27648
	v_bfe_u32 v157, v163, 16, 1
	v_add3_u32 v163, v163, v157, s52
	ds_write_b16_d16_hi v155, v163 offset:36864
	v_bfe_u32 v157, v164, 16, 1
	v_add3_u32 v164, v164, v157, s52
	ds_write_b16_d16_hi v155, v164 offset:46080
	s_waitcnt vmcnt(2)
	v_bfe_u32 v209, v212, 16, 1
	v_add3_u32 v212, v212, v209, s52
	ds_write_b16_d16_hi v207, v212
	s_waitcnt vmcnt(1)
	v_mul_f32_e32 v213, 0x3e000000, v213
	v_bfe_u32 v209, v213, 16, 1
	v_add3_u32 v213, v213, v209, s52
	ds_write_b16_d16_hi v207, v213 offset:9216
	s_waitcnt vmcnt(0)
	v_bfe_u32 v209, v214, 16, 1
	v_add3_u32 v214, v214, v209, s52
	ds_write_b16_d16_hi v208, v214 offset:27648
	v_bfe_u32 v209, v215, 16, 1
	v_add3_u32 v215, v215, v209, s52
	ds_write_b16_d16_hi v207, v215 offset:36864
	v_bfe_u32 v209, v216, 16, 1
	v_add3_u32 v216, v216, v209, s52
	ds_write_b16_d16_hi v207, v216 offset:46080

.LBB0_975:
	v_mov_b32_e32 v114, v2
	v_ashrrev_i32_e32 v115, 6, v114
	v_lshlrev_b32_e32 v116, 2, v115
	ds_read_b32 v116, v116 offset:46592
	v_mad_u64_u32 v[122:123], s[44:45], v115, s33, v[28:29]
	v_add_u32_e32 v124, 0x100, v2
	v_ashrrev_i32_e32 v125, 6, v124
	v_lshlrev_b32_e32 v126, 2, v125
	ds_read_b32 v126, v126 offset:46592
	v_mad_u64_u32 v[132:133], s[44:45], v125, s33, v[28:29]
	v_add_u32_e32 v134, 0x200, v2
	v_ashrrev_i32_e32 v135, 6, v134
	v_lshlrev_b32_e32 v136, 2, v135
	ds_read_b32 v136, v136 offset:46592
	v_mad_u64_u32 v[142:143], s[44:45], v135, s33, v[28:29]
	v_add_u32_e32 v152, 0x300, v2
	v_ashrrev_i32_e32 v153, 6, v152
	v_lshlrev_b32_e32 v154, 2, v153
	ds_read_b32 v154, v154 offset:46592
	v_mad_u64_u32 v[160:161], s[44:45], v153, s33, v[28:29]
	v_add_u32_e32 v162, 0x400, v2
	v_ashrrev_i32_e32 v163, 6, v162
	v_lshlrev_b32_e32 v164, 2, v163
	ds_read_b32 v164, v164 offset:46592
	v_mad_u64_u32 v[170:171], s[44:45], v163, s33, v[28:29]
	v_add_u32_e32 v204, 0x500, v2
	v_ashrrev_i32_e32 v205, 6, v204
	v_lshlrev_b32_e32 v206, 2, v205
	ds_read_b32 v206, v206 offset:46592
	v_mad_u64_u32 v[212:213], s[44:45], v205, s33, v[28:29]
	v_add_u32_e32 v214, 0x600, v2
	v_ashrrev_i32_e32 v215, 6, v214
	v_lshlrev_b32_e32 v216, 2, v215
	ds_read_b32 v216, v216 offset:46592
	v_mad_u64_u32 v[222:223], s[44:45], v215, s33, v[28:29]
	v_add_u32_e32 v234, 0x700, v2
	v_ashrrev_i32_e32 v235, 6, v234
	v_lshlrev_b32_e32 v236, 2, v235
	ds_read_b32 v236, v236 offset:46592
	v_mad_u64_u32 v[242:243], s[44:45], v235, s33, v[28:29]
	s_waitcnt lgkmcnt(7)
	v_ashrrev_i32_e32 v117, 31, v116
	v_lshlrev_b64 v[116:117], 11, v[116:117]
	v_lshl_add_u64 v[116:117], v[0:1], 0, v[116:117]
	global_load_dword v118, v[116:117], off offset:1536
	global_load_dword v121, v[116:117], off offset:1024
	s_waitcnt lgkmcnt(6)
	v_ashrrev_i32_e32 v127, 31, v126
	v_lshlrev_b64 v[126:127], 11, v[126:127]
	v_lshl_add_u64 v[126:127], v[0:1], 0, v[126:127]
	global_load_dword v128, v[126:127], off offset:1536
	global_load_dword v131, v[126:127], off offset:1024
	s_waitcnt lgkmcnt(5)
	v_ashrrev_i32_e32 v137, 31, v136
	v_lshlrev_b64 v[136:137], 11, v[136:137]
	v_lshl_add_u64 v[136:137], v[0:1], 0, v[136:137]
	global_load_dword v138, v[136:137], off offset:1536
	global_load_dword v141, v[136:137], off offset:1024
	s_waitcnt lgkmcnt(4)
	v_ashrrev_i32_e32 v155, 31, v154
	v_lshlrev_b64 v[154:155], 11, v[154:155]
	v_lshl_add_u64 v[154:155], v[0:1], 0, v[154:155]
	global_load_dword v156, v[154:155], off offset:1536
	global_load_dword v159, v[154:155], off offset:1024
	s_waitcnt lgkmcnt(3)
	v_ashrrev_i32_e32 v165, 31, v164
	v_lshlrev_b64 v[164:165], 11, v[164:165]
	v_lshl_add_u64 v[164:165], v[0:1], 0, v[164:165]
	global_load_dword v166, v[164:165], off offset:1536
	global_load_dword v169, v[164:165], off offset:1024
	s_waitcnt lgkmcnt(2)
	v_ashrrev_i32_e32 v207, 31, v206
	v_lshlrev_b64 v[206:207], 11, v[206:207]
	v_lshl_add_u64 v[206:207], v[0:1], 0, v[206:207]
	global_load_dword v208, v[206:207], off offset:1536
	global_load_dword v211, v[206:207], off offset:1024
	s_waitcnt lgkmcnt(1)
	v_ashrrev_i32_e32 v217, 31, v216
	v_lshlrev_b64 v[216:217], 11, v[216:217]
	v_lshl_add_u64 v[216:217], v[0:1], 0, v[216:217]
	global_load_dword v218, v[216:217], off offset:1536
	global_load_dword v221, v[216:217], off offset:1024
	s_waitcnt lgkmcnt(0)
	v_ashrrev_i32_e32 v237, 31, v236
	v_lshlrev_b64 v[236:237], 11, v[236:237]
	v_lshl_add_u64 v[236:237], v[0:1], 0, v[236:237]
	global_load_dword v238, v[236:237], off offset:1536
	global_load_dword v241, v[236:237], off offset:1024
	s_waitcnt vmcnt(15)
	v_bfe_u32 v119, v118, 16, 1
	v_add3_u32 v120, v118, v119, s52
	ds_write_b16_d16_hi v122, v120
	s_waitcnt vmcnt(14)
	v_bfe_u32 v119, v121, 16, 1
	v_add3_u32 v121, v121, v119, s52
	ds_write_b16_d16_hi v122, v121 offset:9216
	s_waitcnt vmcnt(13)
	v_bfe_u32 v129, v128, 16, 1
	v_add3_u32 v130, v128, v129, s52
	ds_write_b16_d16_hi v132, v130
	s_waitcnt vmcnt(12)
	v_bfe_u32 v129, v131, 16, 1
	v_add3_u32 v131, v131, v129, s52
	ds_write_b16_d16_hi v132, v131 offset:9216
	s_waitcnt vmcnt(11)
	v_bfe_u32 v139, v138, 16, 1
	v_add3_u32 v140, v138, v139, s52
	ds_write_b16_d16_hi v142, v140
	s_waitcnt vmcnt(10)
	v_bfe_u32 v139, v141, 16, 1
	v_add3_u32 v141, v141, v139, s52
	ds_write_b16_d16_hi v142, v141 offset:9216
	s_waitcnt vmcnt(9)
	v_bfe_u32 v157, v156, 16, 1
	v_add3_u32 v158, v156, v157, s52
	ds_write_b16_d16_hi v160, v158
	s_waitcnt vmcnt(8)
	v_bfe_u32 v157, v159, 16, 1
	v_add3_u32 v159, v159, v157, s52
	ds_write_b16_d16_hi v160, v159 offset:9216
	s_waitcnt vmcnt(7)
	v_bfe_u32 v167, v166, 16, 1
	v_add3_u32 v168, v166, v167, s52
	ds_write_b16_d16_hi v170, v168
	s_waitcnt vmcnt(6)
	v_bfe_u32 v167, v169, 16, 1
	v_add3_u32 v169, v169, v167, s52
	ds_write_b16_d16_hi v170, v169 offset:9216
	s_waitcnt vmcnt(5)
	v_bfe_u32 v209, v208, 16, 1
	v_add3_u32 v210, v208, v209, s52
	ds_write_b16_d16_hi v212, v210
	s_waitcnt vmcnt(4)
	v_bfe_u32 v209, v211, 16, 1
	v_add3_u32 v211, v211, v209, s52
	ds_write_b16_d16_hi v212, v211 offset:9216
	s_waitcnt vmcnt(3)
	v_bfe_u32 v219, v218, 16, 1
	v_add3_u32 v220, v218, v219, s52
	ds_write_b16_d16_hi v222, v220
	s_waitcnt vmcnt(2)
	v_bfe_u32 v219, v221, 16, 1
	v_add3_u32 v221, v221, v219, s52
	ds_write_b16_d16_hi v222, v221 offset:9216
	s_waitcnt vmcnt(1)
	v_bfe_u32 v239, v238, 16, 1
	v_add3_u32 v240, v238, v239, s52
	ds_write_b16_d16_hi v242, v240
	s_waitcnt vmcnt(0)
	v_bfe_u32 v239, v241, 16, 1
	v_add3_u32 v241, v241, v239, s52
	ds_write_b16_d16_hi v242, v241 offset:9216
	v_add_u32_e32 v114, 0x800, v2
	v_ashrrev_i32_e32 v115, 6, v114
	v_lshlrev_b32_e32 v116, 2, v115
	ds_read_b32 v116, v116 offset:46592
	v_mad_u64_u32 v[122:123], s[44:45], v115, s33, v[28:29]
	v_add_u32_e32 v124, 0x900, v2
	v_ashrrev_i32_e32 v125, 6, v124
	v_lshlrev_b32_e32 v126, 2, v125
	ds_read_b32 v126, v126 offset:46592
	v_mad_u64_u32 v[132:133], s[44:45], v125, s33, v[28:29]
	v_add_u32_e32 v134, 0xa00, v2
	v_ashrrev_i32_e32 v135, 6, v134
	v_lshlrev_b32_e32 v136, 2, v135
	ds_read_b32 v136, v136 offset:46592
	v_mad_u64_u32 v[142:143], s[44:45], v135, s33, v[28:29]
	v_add_u32_e32 v152, 0xb00, v2
	v_ashrrev_i32_e32 v153, 6, v152
	v_lshlrev_b32_e32 v154, 2, v153
	ds_read_b32 v154, v154 offset:46592
	v_mad_u64_u32 v[160:161], s[44:45], v153, s33, v[28:29]
	v_add_u32_e32 v162, 0xc00, v2
	v_ashrrev_i32_e32 v163, 6, v162
	v_lshlrev_b32_e32 v164, 2, v163
	ds_read_b32 v164, v164 offset:46592
	v_mad_u64_u32 v[170:171], s[44:45], v163, s33, v[28:29]
	v_add_u32_e32 v204, 0xd00, v2
	v_ashrrev_i32_e32 v205, 6, v204
	v_lshlrev_b32_e32 v206, 2, v205
	ds_read_b32 v206, v206 offset:46592
	v_mad_u64_u32 v[212:213], s[44:45], v205, s33, v[28:29]
	v_add_u32_e32 v214, 0xe00, v2
	v_ashrrev_i32_e32 v215, 6, v214
	v_lshlrev_b32_e32 v216, 2, v215
	ds_read_b32 v216, v216 offset:46592
	v_mad_u64_u32 v[222:223], s[44:45], v215, s33, v[28:29]
	v_add_u32_e32 v234, 0xf00, v2
	v_ashrrev_i32_e32 v235, 6, v234
	v_lshlrev_b32_e32 v236, 2, v235
	ds_read_b32 v236, v236 offset:46592
	v_mad_u64_u32 v[242:243], s[44:45], v235, s33, v[28:29]
	s_waitcnt lgkmcnt(7)
	v_ashrrev_i32_e32 v117, 31, v116
	v_lshlrev_b64 v[116:117], 11, v[116:117]
	v_lshl_add_u64 v[116:117], v[0:1], 0, v[116:117]
	global_load_dword v118, v[116:117], off offset:1536
	global_load_dword v121, v[116:117], off offset:1024
	s_waitcnt lgkmcnt(6)
	v_ashrrev_i32_e32 v127, 31, v126
	v_lshlrev_b64 v[126:127], 11, v[126:127]
	v_lshl_add_u64 v[126:127], v[0:1], 0, v[126:127]
	global_load_dword v128, v[126:127], off offset:1536
	global_load_dword v131, v[126:127], off offset:1024
	s_waitcnt lgkmcnt(5)
	v_ashrrev_i32_e32 v137, 31, v136
	v_lshlrev_b64 v[136:137], 11, v[136:137]
	v_lshl_add_u64 v[136:137], v[0:1], 0, v[136:137]
	global_load_dword v138, v[136:137], off offset:1536
	global_load_dword v141, v[136:137], off offset:1024
	s_waitcnt lgkmcnt(4)
	v_ashrrev_i32_e32 v155, 31, v154
	v_lshlrev_b64 v[154:155], 11, v[154:155]
	v_lshl_add_u64 v[154:155], v[0:1], 0, v[154:155]
	global_load_dword v156, v[154:155], off offset:1536
	global_load_dword v159, v[154:155], off offset:1024
	s_waitcnt lgkmcnt(3)
	v_ashrrev_i32_e32 v165, 31, v164
	v_lshlrev_b64 v[164:165], 11, v[164:165]
	v_lshl_add_u64 v[164:165], v[0:1], 0, v[164:165]
	global_load_dword v166, v[164:165], off offset:1536
	global_load_dword v169, v[164:165], off offset:1024
	s_waitcnt lgkmcnt(2)
	v_ashrrev_i32_e32 v207, 31, v206
	v_lshlrev_b64 v[206:207], 11, v[206:207]
	v_lshl_add_u64 v[206:207], v[0:1], 0, v[206:207]
	global_load_dword v208, v[206:207], off offset:1536
	global_load_dword v211, v[206:207], off offset:1024
	s_waitcnt lgkmcnt(1)
	v_ashrrev_i32_e32 v217, 31, v216
	v_lshlrev_b64 v[216:217], 11, v[216:217]
	v_lshl_add_u64 v[216:217], v[0:1], 0, v[216:217]
	global_load_dword v218, v[216:217], off offset:1536
	global_load_dword v221, v[216:217], off offset:1024
	s_waitcnt lgkmcnt(0)
	v_ashrrev_i32_e32 v237, 31, v236
	v_lshlrev_b64 v[236:237], 11, v[236:237]
	v_lshl_add_u64 v[236:237], v[0:1], 0, v[236:237]
	global_load_dword v238, v[236:237], off offset:1536
	global_load_dword v241, v[236:237], off offset:1024
	s_waitcnt vmcnt(15)
	v_bfe_u32 v119, v118, 16, 1
	v_add3_u32 v120, v118, v119, s52
	ds_write_b16_d16_hi v122, v120
	s_waitcnt vmcnt(14)
	v_bfe_u32 v119, v121, 16, 1
	v_add3_u32 v121, v121, v119, s52
	ds_write_b16_d16_hi v122, v121 offset:9216
	s_waitcnt vmcnt(13)
	v_bfe_u32 v129, v128, 16, 1
	v_add3_u32 v130, v128, v129, s52
	ds_write_b16_d16_hi v132, v130
	s_waitcnt vmcnt(12)
	v_bfe_u32 v129, v131, 16, 1
	v_add3_u32 v131, v131, v129, s52
	ds_write_b16_d16_hi v132, v131 offset:9216
	s_waitcnt vmcnt(11)
	v_bfe_u32 v139, v138, 16, 1
	v_add3_u32 v140, v138, v139, s52
	ds_write_b16_d16_hi v142, v140
	s_waitcnt vmcnt(10)
	v_bfe_u32 v139, v141, 16, 1
	v_add3_u32 v141, v141, v139, s52
	ds_write_b16_d16_hi v142, v141 offset:9216
	s_waitcnt vmcnt(9)
	v_bfe_u32 v157, v156, 16, 1
	v_add3_u32 v158, v156, v157, s52
	ds_write_b16_d16_hi v160, v158
	s_waitcnt vmcnt(8)
	v_bfe_u32 v157, v159, 16, 1
	v_add3_u32 v159, v159, v157, s52
	ds_write_b16_d16_hi v160, v159 offset:9216
	s_waitcnt vmcnt(7)
	v_bfe_u32 v167, v166, 16, 1
	v_add3_u32 v168, v166, v167, s52
	ds_write_b16_d16_hi v170, v168
	s_waitcnt vmcnt(6)
	v_bfe_u32 v167, v169, 16, 1
	v_add3_u32 v169, v169, v167, s52
	ds_write_b16_d16_hi v170, v169 offset:9216
	s_waitcnt vmcnt(5)
	v_bfe_u32 v209, v208, 16, 1
	v_add3_u32 v210, v208, v209, s52
	ds_write_b16_d16_hi v212, v210
	s_waitcnt vmcnt(4)
	v_bfe_u32 v209, v211, 16, 1
	v_add3_u32 v211, v211, v209, s52
	ds_write_b16_d16_hi v212, v211 offset:9216
	s_waitcnt vmcnt(3)
	v_bfe_u32 v219, v218, 16, 1
	v_add3_u32 v220, v218, v219, s52
	ds_write_b16_d16_hi v222, v220
	s_waitcnt vmcnt(2)
	v_bfe_u32 v219, v221, 16, 1
	v_add3_u32 v221, v221, v219, s52
	ds_write_b16_d16_hi v222, v221 offset:9216
	s_waitcnt vmcnt(1)
	v_bfe_u32 v239, v238, 16, 1
	v_add3_u32 v240, v238, v239, s52
	ds_write_b16_d16_hi v242, v240
	s_waitcnt vmcnt(0)
	v_bfe_u32 v239, v241, 16, 1
	v_add3_u32 v241, v241, v239, s52
	ds_write_b16_d16_hi v242, v241 offset:9216

.LBB0_981:
	v_mov_b32_e32 v114, v36
	v_add_u32_e32 v115, 0x100, v114
	v_ashrrev_i32_e32 v122, 6, v114
	v_ashrrev_i32_e32 v117, 6, v115
	v_lshlrev_b32_e32 v118, 2, v122
	v_lshlrev_b32_e32 v119, 2, v117
	ds_read_b32 v118, v118 offset:46592
	ds_read_b32 v120, v119 offset:46592
	v_lshl_add_u32 v123, v122, 1, v25
	v_lshl_add_u32 v117, v117, 1, v25
	v_add_u32_e32 v126, 0x200, v36
	v_add_u32_e32 v127, 0x100, v126
	v_ashrrev_i32_e32 v134, 6, v126
	v_ashrrev_i32_e32 v129, 6, v127
	v_lshlrev_b32_e32 v130, 2, v134
	v_lshlrev_b32_e32 v131, 2, v129
	ds_read_b32 v130, v130 offset:46592
	ds_read_b32 v132, v131 offset:46592
	v_lshl_add_u32 v135, v134, 1, v25
	v_lshl_add_u32 v129, v129, 1, v25
	v_add_u32_e32 v152, 0x400, v36
	v_add_u32_e32 v153, 0x100, v152
	v_ashrrev_i32_e32 v160, 6, v152
	v_ashrrev_i32_e32 v155, 6, v153
	v_lshlrev_b32_e32 v156, 2, v160
	v_lshlrev_b32_e32 v157, 2, v155
	ds_read_b32 v156, v156 offset:46592
	ds_read_b32 v158, v157 offset:46592
	v_lshl_add_u32 v161, v160, 1, v25
	v_lshl_add_u32 v155, v155, 1, v25
	v_add_u32_e32 v204, 0x600, v36
	v_add_u32_e32 v205, 0x100, v204
	v_ashrrev_i32_e32 v212, 6, v204
	v_ashrrev_i32_e32 v207, 6, v205
	v_lshlrev_b32_e32 v208, 2, v212
	v_lshlrev_b32_e32 v209, 2, v207
	ds_read_b32 v208, v208 offset:46592
	ds_read_b32 v210, v209 offset:46592
	v_lshl_add_u32 v213, v212, 1, v25
	v_lshl_add_u32 v207, v207, 1, v25
	s_waitcnt lgkmcnt(7)
	v_ashrrev_i32_e32 v119, 31, v118
	s_waitcnt lgkmcnt(6)
	v_ashrrev_i32_e32 v121, 31, v120
	v_lshlrev_b64 v[120:121], 11, v[120:121]
	v_lshlrev_b64 v[118:119], 11, v[118:119]
	v_lshl_add_u64 v[118:119], v[34:35], 0, v[118:119]
	v_lshl_add_u64 v[120:121], v[34:35], 0, v[120:121]
	global_load_dword v124, v[120:121], off
	global_load_dword v125, v[118:119], off
	s_waitcnt lgkmcnt(5)
	v_ashrrev_i32_e32 v131, 31, v130
	s_waitcnt lgkmcnt(4)
	v_ashrrev_i32_e32 v133, 31, v132
	v_lshlrev_b64 v[132:133], 11, v[132:133]
	v_lshlrev_b64 v[130:131], 11, v[130:131]
	v_lshl_add_u64 v[130:131], v[34:35], 0, v[130:131]
	v_lshl_add_u64 v[132:133], v[34:35], 0, v[132:133]
	global_load_dword v136, v[132:133], off
	global_load_dword v137, v[130:131], off
	s_waitcnt lgkmcnt(3)
	v_ashrrev_i32_e32 v157, 31, v156
	s_waitcnt lgkmcnt(2)
	v_ashrrev_i32_e32 v159, 31, v158
	v_lshlrev_b64 v[158:159], 11, v[158:159]
	v_lshlrev_b64 v[156:157], 11, v[156:157]
	v_lshl_add_u64 v[156:157], v[34:35], 0, v[156:157]
	v_lshl_add_u64 v[158:159], v[34:35], 0, v[158:159]
	global_load_dword v162, v[158:159], off
	global_load_dword v163, v[156:157], off
	s_waitcnt lgkmcnt(1)
	v_ashrrev_i32_e32 v209, 31, v208
	s_waitcnt lgkmcnt(0)
	v_ashrrev_i32_e32 v211, 31, v210
	v_lshlrev_b64 v[210:211], 11, v[210:211]
	v_lshlrev_b64 v[208:209], 11, v[208:209]
	v_lshl_add_u64 v[208:209], v[34:35], 0, v[208:209]
	v_lshl_add_u64 v[210:211], v[34:35], 0, v[210:211]
	global_load_dword v214, v[210:211], off
	global_load_dword v215, v[208:209], off
	s_waitcnt vmcnt(7)
	v_and_b32_sdwa v121, v124, v175 dst_sel:DWORD dst_unused:UNUSED_PAD src0_sel:WORD_1 src1_sel:DWORD
	s_waitcnt vmcnt(6)
	v_and_b32_sdwa v122, v125, v175 dst_sel:DWORD dst_unused:UNUSED_PAD src0_sel:WORD_1 src1_sel:DWORD
	v_add3_u32 v125, v125, v122, s52
	v_add3_u32 v124, v124, v121, s52
	ds_write_b16_d16_hi v123, v125 offset:27648
	ds_write_b16_d16_hi v117, v124 offset:27648
	s_waitcnt vmcnt(5)
	v_and_b32_sdwa v133, v136, v175 dst_sel:DWORD dst_unused:UNUSED_PAD src0_sel:WORD_1 src1_sel:DWORD
	s_waitcnt vmcnt(4)
	v_and_b32_sdwa v134, v137, v175 dst_sel:DWORD dst_unused:UNUSED_PAD src0_sel:WORD_1 src1_sel:DWORD
	v_add3_u32 v137, v137, v134, s52
	v_add3_u32 v136, v136, v133, s52
	ds_write_b16_d16_hi v135, v137 offset:27648
	ds_write_b16_d16_hi v129, v136 offset:27648
	s_waitcnt vmcnt(3)
	v_and_b32_sdwa v159, v162, v175 dst_sel:DWORD dst_unused:UNUSED_PAD src0_sel:WORD_1 src1_sel:DWORD
	s_waitcnt vmcnt(2)
	v_and_b32_sdwa v160, v163, v175 dst_sel:DWORD dst_unused:UNUSED_PAD src0_sel:WORD_1 src1_sel:DWORD
	v_add3_u32 v163, v163, v160, s52
	v_add3_u32 v162, v162, v159, s52
	ds_write_b16_d16_hi v161, v163 offset:27648
	ds_write_b16_d16_hi v155, v162 offset:27648
	s_waitcnt vmcnt(1)
	v_and_b32_sdwa v211, v214, v175 dst_sel:DWORD dst_unused:UNUSED_PAD src0_sel:WORD_1 src1_sel:DWORD
	s_waitcnt vmcnt(0)
	v_and_b32_sdwa v212, v215, v175 dst_sel:DWORD dst_unused:UNUSED_PAD src0_sel:WORD_1 src1_sel:DWORD
	v_add3_u32 v215, v215, v212, s52
	v_add3_u32 v214, v214, v211, s52
	ds_write_b16_d16_hi v213, v215 offset:27648
	ds_write_b16_d16_hi v207, v214 offset:27648
	v_add_u32_e32 v114, 0x800, v36
	v_add_u32_e32 v115, 0x100, v114
	v_ashrrev_i32_e32 v122, 6, v114
	v_ashrrev_i32_e32 v117, 6, v115
	v_lshlrev_b32_e32 v118, 2, v122
	v_lshlrev_b32_e32 v119, 2, v117
	ds_read_b32 v118, v118 offset:46592
	ds_read_b32 v120, v119 offset:46592
	v_lshl_add_u32 v123, v122, 1, v25
	v_lshl_add_u32 v117, v117, 1, v25
	v_add_u32_e32 v126, 0xa00, v36
	v_add_u32_e32 v127, 0x100, v126
	v_ashrrev_i32_e32 v134, 6, v126
	v_ashrrev_i32_e32 v129, 6, v127
	v_lshlrev_b32_e32 v130, 2, v134
	v_lshlrev_b32_e32 v131, 2, v129
	ds_read_b32 v130, v130 offset:46592
	ds_read_b32 v132, v131 offset:46592
	v_lshl_add_u32 v135, v134, 1, v25
	v_lshl_add_u32 v129, v129, 1, v25
	v_add_u32_e32 v152, 0xc00, v36
	v_add_u32_e32 v153, 0x100, v152
	v_ashrrev_i32_e32 v160, 6, v152
	v_ashrrev_i32_e32 v155, 6, v153
	v_lshlrev_b32_e32 v156, 2, v160
	v_lshlrev_b32_e32 v157, 2, v155
	ds_read_b32 v156, v156 offset:46592
	ds_read_b32 v158, v157 offset:46592
	v_lshl_add_u32 v161, v160, 1, v25
	v_lshl_add_u32 v155, v155, 1, v25
	v_add_u32_e32 v204, 0xe00, v36
	v_add_u32_e32 v205, 0x100, v204
	v_ashrrev_i32_e32 v212, 6, v204
	v_ashrrev_i32_e32 v207, 6, v205
	v_lshlrev_b32_e32 v208, 2, v212
	v_lshlrev_b32_e32 v209, 2, v207
	ds_read_b32 v208, v208 offset:46592
	ds_read_b32 v210, v209 offset:46592
	v_lshl_add_u32 v213, v212, 1, v25
	v_lshl_add_u32 v207, v207, 1, v25
	s_waitcnt lgkmcnt(7)
	v_ashrrev_i32_e32 v119, 31, v118
	s_waitcnt lgkmcnt(6)
	v_ashrrev_i32_e32 v121, 31, v120
	v_lshlrev_b64 v[120:121], 11, v[120:121]
	v_lshlrev_b64 v[118:119], 11, v[118:119]
	v_lshl_add_u64 v[118:119], v[34:35], 0, v[118:119]
	v_lshl_add_u64 v[120:121], v[34:35], 0, v[120:121]
	global_load_dword v124, v[120:121], off
	global_load_dword v125, v[118:119], off
	s_waitcnt lgkmcnt(5)
	v_ashrrev_i32_e32 v131, 31, v130
	s_waitcnt lgkmcnt(4)
	v_ashrrev_i32_e32 v133, 31, v132
	v_lshlrev_b64 v[132:133], 11, v[132:133]
	v_lshlrev_b64 v[130:131], 11, v[130:131]
	v_lshl_add_u64 v[130:131], v[34:35], 0, v[130:131]
	v_lshl_add_u64 v[132:133], v[34:35], 0, v[132:133]
	global_load_dword v136, v[132:133], off
	global_load_dword v137, v[130:131], off
	s_waitcnt lgkmcnt(3)
	v_ashrrev_i32_e32 v157, 31, v156
	s_waitcnt lgkmcnt(2)
	v_ashrrev_i32_e32 v159, 31, v158
	v_lshlrev_b64 v[158:159], 11, v[158:159]
	v_lshlrev_b64 v[156:157], 11, v[156:157]
	v_lshl_add_u64 v[156:157], v[34:35], 0, v[156:157]
	v_lshl_add_u64 v[158:159], v[34:35], 0, v[158:159]
	global_load_dword v162, v[158:159], off
	global_load_dword v163, v[156:157], off
	s_waitcnt lgkmcnt(1)
	v_ashrrev_i32_e32 v209, 31, v208
	s_waitcnt lgkmcnt(0)
	v_ashrrev_i32_e32 v211, 31, v210
	v_lshlrev_b64 v[210:211], 11, v[210:211]
	v_lshlrev_b64 v[208:209], 11, v[208:209]
	v_lshl_add_u64 v[208:209], v[34:35], 0, v[208:209]
	v_lshl_add_u64 v[210:211], v[34:35], 0, v[210:211]
	global_load_dword v214, v[210:211], off
	global_load_dword v215, v[208:209], off
	s_waitcnt vmcnt(7)
	v_and_b32_sdwa v121, v124, v175 dst_sel:DWORD dst_unused:UNUSED_PAD src0_sel:WORD_1 src1_sel:DWORD
	s_waitcnt vmcnt(6)
	v_and_b32_sdwa v122, v125, v175 dst_sel:DWORD dst_unused:UNUSED_PAD src0_sel:WORD_1 src1_sel:DWORD
	v_add3_u32 v125, v125, v122, s52
	v_add3_u32 v124, v124, v121, s52
	ds_write_b16_d16_hi v123, v125 offset:27648
	ds_write_b16_d16_hi v117, v124 offset:27648
	s_waitcnt vmcnt(5)
	v_and_b32_sdwa v133, v136, v175 dst_sel:DWORD dst_unused:UNUSED_PAD src0_sel:WORD_1 src1_sel:DWORD
	s_waitcnt vmcnt(4)
	v_and_b32_sdwa v134, v137, v175 dst_sel:DWORD dst_unused:UNUSED_PAD src0_sel:WORD_1 src1_sel:DWORD
	v_add3_u32 v137, v137, v134, s52
	v_add3_u32 v136, v136, v133, s52
	ds_write_b16_d16_hi v135, v137 offset:27648
	ds_write_b16_d16_hi v129, v136 offset:27648
	s_waitcnt vmcnt(3)
	v_and_b32_sdwa v159, v162, v175 dst_sel:DWORD dst_unused:UNUSED_PAD src0_sel:WORD_1 src1_sel:DWORD
	s_waitcnt vmcnt(2)
	v_and_b32_sdwa v160, v163, v175 dst_sel:DWORD dst_unused:UNUSED_PAD src0_sel:WORD_1 src1_sel:DWORD
	v_add3_u32 v163, v163, v160, s52
	v_add3_u32 v162, v162, v159, s52
	ds_write_b16_d16_hi v161, v163 offset:27648
	ds_write_b16_d16_hi v155, v162 offset:27648
	s_waitcnt vmcnt(1)
	v_and_b32_sdwa v211, v214, v175 dst_sel:DWORD dst_unused:UNUSED_PAD src0_sel:WORD_1 src1_sel:DWORD
	s_waitcnt vmcnt(0)
	v_and_b32_sdwa v212, v215, v175 dst_sel:DWORD dst_unused:UNUSED_PAD src0_sel:WORD_1 src1_sel:DWORD
	v_add3_u32 v215, v215, v212, s52
	v_add3_u32 v214, v214, v211, s52
	ds_write_b16_d16_hi v213, v215 offset:27648
	ds_write_b16_d16_hi v207, v214 offset:27648
	s_or_b64 exec, exec, s[46:47]
	v_readlane_b32 s46, v249, 61
	v_readlane_b32 s47, v249, 62
	s_orn2_b64 s[46:47], s[46:47], exec
	v_mov_b32_e32 v36, v101

.LBB0_1019:
	v_mov_b32_e32 v114, v50
	v_add_u32_e32 v115, 0x100, v114
	v_ashrrev_i32_e32 v117, 31, v114
	v_mov_b32_e32 v116, v114
	v_ashrrev_i32_e32 v119, 31, v115
	v_mov_b32_e32 v118, v115
	v_lshl_add_u64 v[116:117], v[116:117], 2, s[50:51]
	v_lshl_add_u64 v[118:119], v[118:119], 2, s[50:51]
	global_load_dword v120, v[116:117], off
	global_load_dword v121, v[118:119], off
	v_ashrrev_i32_e32 v122, 6, v114
	v_ashrrev_i32_e32 v124, 6, v115
	v_mad_u64_u32 v[122:123], vcc, v122, s33, v[28:29]
	v_mad_u64_u32 v[124:125], vcc, v124, s33, v[28:29]
	v_add_u32_e32 v126, 0x200, v50
	v_add_u32_e32 v127, 0x100, v126
	v_ashrrev_i32_e32 v129, 31, v126
	v_mov_b32_e32 v128, v126
	v_ashrrev_i32_e32 v131, 31, v127
	v_mov_b32_e32 v130, v127
	v_lshl_add_u64 v[128:129], v[128:129], 2, s[50:51]
	v_lshl_add_u64 v[130:131], v[130:131], 2, s[50:51]
	global_load_dword v132, v[128:129], off
	global_load_dword v133, v[130:131], off
	v_ashrrev_i32_e32 v134, 6, v126
	v_ashrrev_i32_e32 v136, 6, v127
	v_mad_u64_u32 v[134:135], vcc, v134, s33, v[28:29]
	v_mad_u64_u32 v[136:137], vcc, v136, s33, v[28:29]
	v_add_u32_e32 v152, 0x400, v50
	v_add_u32_e32 v153, 0x100, v152
	v_ashrrev_i32_e32 v155, 31, v152
	v_mov_b32_e32 v154, v152
	v_ashrrev_i32_e32 v157, 31, v153
	v_mov_b32_e32 v156, v153
	v_lshl_add_u64 v[154:155], v[154:155], 2, s[50:51]
	v_lshl_add_u64 v[156:157], v[156:157], 2, s[50:51]
	global_load_dword v158, v[154:155], off
	global_load_dword v159, v[156:157], off
	v_ashrrev_i32_e32 v160, 6, v152
	v_ashrrev_i32_e32 v162, 6, v153
	v_mad_u64_u32 v[160:161], vcc, v160, s33, v[28:29]
	v_mad_u64_u32 v[162:163], vcc, v162, s33, v[28:29]
	v_add_u32_e32 v204, 0x600, v50
	v_add_u32_e32 v205, 0x100, v204
	v_ashrrev_i32_e32 v207, 31, v204
	v_mov_b32_e32 v206, v204
	v_ashrrev_i32_e32 v209, 31, v205
	v_mov_b32_e32 v208, v205
	v_lshl_add_u64 v[206:207], v[206:207], 2, s[50:51]
	v_lshl_add_u64 v[208:209], v[208:209], 2, s[50:51]
	global_load_dword v210, v[206:207], off
	global_load_dword v211, v[208:209], off
	v_ashrrev_i32_e32 v212, 6, v204
	v_ashrrev_i32_e32 v214, 6, v205
	v_mad_u64_u32 v[212:213], vcc, v212, s33, v[28:29]
	v_mad_u64_u32 v[214:215], vcc, v214, s33, v[28:29]
	s_waitcnt vmcnt(7)
	v_and_b32_sdwa v116, v120, v175 dst_sel:DWORD dst_unused:UNUSED_PAD src0_sel:WORD_1 src1_sel:DWORD
	s_waitcnt vmcnt(6)
	v_and_b32_sdwa v118, v121, v175 dst_sel:DWORD dst_unused:UNUSED_PAD src0_sel:WORD_1 src1_sel:DWORD
	v_add3_u32 v120, v120, v116, s52
	v_add3_u32 v121, v121, v118, s52
	ds_write_b16_d16_hi v122, v120 offset:36864
	ds_write_b16_d16_hi v124, v121 offset:36864
	s_waitcnt vmcnt(5)
	v_and_b32_sdwa v128, v132, v175 dst_sel:DWORD dst_unused:UNUSED_PAD src0_sel:WORD_1 src1_sel:DWORD
	s_waitcnt vmcnt(4)
	v_and_b32_sdwa v130, v133, v175 dst_sel:DWORD dst_unused:UNUSED_PAD src0_sel:WORD_1 src1_sel:DWORD
	v_add3_u32 v132, v132, v128, s52
	v_add3_u32 v133, v133, v130, s52
	ds_write_b16_d16_hi v134, v132 offset:36864
	ds_write_b16_d16_hi v136, v133 offset:36864
	s_waitcnt vmcnt(3)
	v_and_b32_sdwa v154, v158, v175 dst_sel:DWORD dst_unused:UNUSED_PAD src0_sel:WORD_1 src1_sel:DWORD
	s_waitcnt vmcnt(2)
	v_and_b32_sdwa v156, v159, v175 dst_sel:DWORD dst_unused:UNUSED_PAD src0_sel:WORD_1 src1_sel:DWORD
	v_add3_u32 v158, v158, v154, s52
	v_add3_u32 v159, v159, v156, s52
	ds_write_b16_d16_hi v160, v158 offset:36864
	ds_write_b16_d16_hi v162, v159 offset:36864
	s_waitcnt vmcnt(1)
	v_and_b32_sdwa v206, v210, v175 dst_sel:DWORD dst_unused:UNUSED_PAD src0_sel:WORD_1 src1_sel:DWORD
	s_waitcnt vmcnt(0)
	v_and_b32_sdwa v208, v211, v175 dst_sel:DWORD dst_unused:UNUSED_PAD src0_sel:WORD_1 src1_sel:DWORD
	v_add3_u32 v210, v210, v206, s52
	v_add3_u32 v211, v211, v208, s52
	ds_write_b16_d16_hi v212, v210 offset:36864
	ds_write_b16_d16_hi v214, v211 offset:36864
	v_add_u32_e32 v114, 0x800, v50
	v_add_u32_e32 v115, 0x100, v114
	v_ashrrev_i32_e32 v117, 31, v114
	v_mov_b32_e32 v116, v114
	v_ashrrev_i32_e32 v119, 31, v115
	v_mov_b32_e32 v118, v115
	v_lshl_add_u64 v[116:117], v[116:117], 2, s[50:51]
	v_lshl_add_u64 v[118:119], v[118:119], 2, s[50:51]
	global_load_dword v120, v[116:117], off
	global_load_dword v121, v[118:119], off
	v_ashrrev_i32_e32 v122, 6, v114
	v_ashrrev_i32_e32 v124, 6, v115
	v_mad_u64_u32 v[122:123], vcc, v122, s33, v[28:29]
	v_mad_u64_u32 v[124:125], vcc, v124, s33, v[28:29]
	v_add_u32_e32 v126, 0xa00, v50
	v_add_u32_e32 v127, 0x100, v126
	v_ashrrev_i32_e32 v129, 31, v126
	v_mov_b32_e32 v128, v126
	v_ashrrev_i32_e32 v131, 31, v127
	v_mov_b32_e32 v130, v127
	v_lshl_add_u64 v[128:129], v[128:129], 2, s[50:51]
	v_lshl_add_u64 v[130:131], v[130:131], 2, s[50:51]
	global_load_dword v132, v[128:129], off
	global_load_dword v133, v[130:131], off
	v_ashrrev_i32_e32 v134, 6, v126
	v_ashrrev_i32_e32 v136, 6, v127
	v_mad_u64_u32 v[134:135], vcc, v134, s33, v[28:29]
	v_mad_u64_u32 v[136:137], vcc, v136, s33, v[28:29]
	v_add_u32_e32 v152, 0xc00, v50
	v_add_u32_e32 v153, 0x100, v152
	v_ashrrev_i32_e32 v155, 31, v152
	v_mov_b32_e32 v154, v152
	v_ashrrev_i32_e32 v157, 31, v153
	v_mov_b32_e32 v156, v153
	v_lshl_add_u64 v[154:155], v[154:155], 2, s[50:51]
	v_lshl_add_u64 v[156:157], v[156:157], 2, s[50:51]
	global_load_dword v158, v[154:155], off
	global_load_dword v159, v[156:157], off
	v_ashrrev_i32_e32 v160, 6, v152
	v_ashrrev_i32_e32 v162, 6, v153
	v_mad_u64_u32 v[160:161], vcc, v160, s33, v[28:29]
	v_mad_u64_u32 v[162:163], vcc, v162, s33, v[28:29]
	v_add_u32_e32 v204, 0xe00, v50
	v_add_u32_e32 v205, 0x100, v204
	v_ashrrev_i32_e32 v207, 31, v204
	v_mov_b32_e32 v206, v204
	v_ashrrev_i32_e32 v209, 31, v205
	v_mov_b32_e32 v208, v205
	v_lshl_add_u64 v[206:207], v[206:207], 2, s[50:51]
	v_lshl_add_u64 v[208:209], v[208:209], 2, s[50:51]
	global_load_dword v210, v[206:207], off
	global_load_dword v211, v[208:209], off
	v_ashrrev_i32_e32 v212, 6, v204
	v_ashrrev_i32_e32 v214, 6, v205
	v_mad_u64_u32 v[212:213], vcc, v212, s33, v[28:29]
	v_mad_u64_u32 v[214:215], vcc, v214, s33, v[28:29]
	s_waitcnt vmcnt(7)
	v_and_b32_sdwa v116, v120, v175 dst_sel:DWORD dst_unused:UNUSED_PAD src0_sel:WORD_1 src1_sel:DWORD
	s_waitcnt vmcnt(6)
	v_and_b32_sdwa v118, v121, v175 dst_sel:DWORD dst_unused:UNUSED_PAD src0_sel:WORD_1 src1_sel:DWORD
	v_add3_u32 v120, v120, v116, s52
	v_add3_u32 v121, v121, v118, s52
	ds_write_b16_d16_hi v122, v120 offset:36864
	ds_write_b16_d16_hi v124, v121 offset:36864
	s_waitcnt vmcnt(5)
	v_and_b32_sdwa v128, v132, v175 dst_sel:DWORD dst_unused:UNUSED_PAD src0_sel:WORD_1 src1_sel:DWORD
	s_waitcnt vmcnt(4)
	v_and_b32_sdwa v130, v133, v175 dst_sel:DWORD dst_unused:UNUSED_PAD src0_sel:WORD_1 src1_sel:DWORD
	v_add3_u32 v132, v132, v128, s52
	v_add3_u32 v133, v133, v130, s52
	ds_write_b16_d16_hi v134, v132 offset:36864
	ds_write_b16_d16_hi v136, v133 offset:36864
	s_waitcnt vmcnt(3)
	v_and_b32_sdwa v154, v158, v175 dst_sel:DWORD dst_unused:UNUSED_PAD src0_sel:WORD_1 src1_sel:DWORD
	s_waitcnt vmcnt(2)
	v_and_b32_sdwa v156, v159, v175 dst_sel:DWORD dst_unused:UNUSED_PAD src0_sel:WORD_1 src1_sel:DWORD
	v_add3_u32 v158, v158, v154, s52
	v_add3_u32 v159, v159, v156, s52
	ds_write_b16_d16_hi v160, v158 offset:36864
	ds_write_b16_d16_hi v162, v159 offset:36864
	s_waitcnt vmcnt(1)
	v_and_b32_sdwa v206, v210, v175 dst_sel:DWORD dst_unused:UNUSED_PAD src0_sel:WORD_1 src1_sel:DWORD
	s_waitcnt vmcnt(0)
	v_and_b32_sdwa v208, v211, v175 dst_sel:DWORD dst_unused:UNUSED_PAD src0_sel:WORD_1 src1_sel:DWORD
	v_add3_u32 v210, v210, v206, s52
	v_add3_u32 v211, v211, v208, s52
	ds_write_b16_d16_hi v212, v210 offset:36864
	ds_write_b16_d16_hi v214, v211 offset:36864
	s_or_b64 exec, exec, s[24:25]
	v_readlane_b32 s24, v249, 61
	v_readlane_b32 s25, v249, 62
	s_orn2_b64 s[24:25], s[24:25], exec
	v_mov_b32_e32 v50, v101
